# MLA fast loop: K/V tile loads in saddr form (SGPR tile base advanced by SALU, constant lane offsets) - no per-tile 64-bit VALU pointer advances
# baseline (speedup 1.0000x reference)
.Lf_entry:
	s_add_u32 s100, s42, 0x3000
	s_addc_u32 s101, s43, 0
	s_mov_b64 s[54:55], s[4:5]
	v_subrev_u32_e32 v255, s42, v202
	v_add_u32_e32 v255, 0xffffd000, v255
	v_subrev_u32_e32 v239, s4, v200
	v_mov_b32_e32 v244, 0
	v_mov_b32_e32 v245, 0
	v_mov_b32_e32 v246, 0
	v_mov_b32_e32 v247, 0
	v_mov_b32_e32 v250, 0
	v_mov_b32_e32 v251, 0
	v_mov_b32_e32 v252, 0
	v_mov_b32_e32 v253, 0
	v_mov_b32_e32 v240, 0
	v_mov_b32_e32 v241, 0
	v_mov_b32_e32 v10, 0
	v_mov_b32_e32 v211, 0
	v_lshlrev_b32_e32 v249, 1, v198
.Lf_960:
	global_load_dwordx4 v[2:5], v255, s[100:101]
	global_load_dwordx4 v[192:195], v239, s[54:55]
	s_add_i32 s33, s24, 1
	s_and_saveexec_b64 s[44:45], s[0:1]
	s_cbranch_execz .Lf_962
	global_load_dwordx4 v[6:9], v249, s[100:101]

.Lf_966:
	s_or_b64 exec, exec, s[44:45]
	s_waitcnt vmcnt(0)
	ds_write_b128 v215, v[192:195] offset:35840
	v_pk_add_f32 v[244:245], v[244:245], v[88:89]
	v_pk_add_f32 v[246:247], v[246:247], v[90:91]
	v_pk_add_f32 v[244:245], v[244:245], v[92:93]
	v_pk_add_f32 v[246:247], v[246:247], v[94:95]
	v_pk_add_f32 v[244:245], v[244:245], v[112:113]
	v_pk_add_f32 v[246:247], v[246:247], v[114:115]
	v_pk_add_f32 v[244:245], v[244:245], v[116:117]
	v_pk_add_f32 v[246:247], v[246:247], v[118:119]
	v_pk_add_f32 v[244:245], v[244:245], v[120:121]
	v_pk_add_f32 v[246:247], v[246:247], v[122:123]
	v_pk_add_f32 v[244:245], v[244:245], v[124:125]
	v_pk_add_f32 v[246:247], v[246:247], v[126:127]
	v_pk_add_f32 v[244:245], v[244:245], v[140:141]
	v_pk_add_f32 v[246:247], v[246:247], v[142:143]
	v_add_f32_e32 v244, v80, v244
	v_add_f32_e32 v246, v106, v246
	v_pk_add_f32 v[250:251], v[250:251], v[12:13]
	v_pk_add_f32 v[252:253], v[252:253], v[14:15]
	v_pk_add_f32 v[250:251], v[250:251], v[82:83]
	v_pk_add_f32 v[252:253], v[252:253], v[84:85]
	v_pk_add_f32 v[250:251], v[250:251], v[96:97]
	v_pk_add_f32 v[252:253], v[252:253], v[98:99]
	v_pk_add_f32 v[250:251], v[250:251], v[100:101]
	v_pk_add_f32 v[252:253], v[252:253], v[102:103]
	v_pk_add_f32 v[250:251], v[250:251], v[104:105]
	v_pk_add_f32 v[252:253], v[252:253], v[128:129]
	v_pk_add_f32 v[250:251], v[250:251], v[130:131]
	v_pk_add_f32 v[252:253], v[252:253], v[132:133]
	v_pk_add_f32 v[250:251], v[250:251], v[134:135]
	v_pk_add_f32 v[252:253], v[252:253], v[136:137]
	v_add_f32_e32 v250, v11, v250
	v_add_f32_e32 v252, v237, v252
	v_pk_add_f32 v[240:241], v[240:241], v[86:87]
	v_pk_add_f32 v[240:241], v[240:241], v[138:139]
	s_add_u32 s100, s100, 0x3000
	s_addc_u32 s101, s101, 0
	s_add_u32 s54, s54, 0x80
	s_addc_u32 s55, s55, 0
	s_cmp_eq_u32 s33, 63
	s_waitcnt lgkmcnt(0)
	s_barrier
	s_cbranch_scc1 .Lf_exit
	global_load_dwordx4 v[2:5], v255, s[100:101]
	global_load_dwordx4 v[192:195], v239, s[54:55]
	s_add_i32 s33, s33, 1
	s_and_saveexec_b64 s[44:45], s[0:1]
	s_cbranch_execz .Lf_962o
	global_load_dwordx4 v[6:9], v249, s[100:101]

.Lf_966o:
	s_or_b64 exec, exec, s[44:45]
	s_waitcnt vmcnt(0)
	ds_write_b128 v215, v[192:195] offset:26624
	v_pk_add_f32 v[244:245], v[244:245], v[88:89]
	v_pk_add_f32 v[246:247], v[246:247], v[90:91]
	v_pk_add_f32 v[244:245], v[244:245], v[92:93]
	v_pk_add_f32 v[246:247], v[246:247], v[94:95]
	v_pk_add_f32 v[244:245], v[244:245], v[112:113]
	v_pk_add_f32 v[246:247], v[246:247], v[114:115]
	v_pk_add_f32 v[244:245], v[244:245], v[116:117]
	v_pk_add_f32 v[246:247], v[246:247], v[118:119]
	v_pk_add_f32 v[244:245], v[244:245], v[120:121]
	v_pk_add_f32 v[246:247], v[246:247], v[122:123]
	v_pk_add_f32 v[244:245], v[244:245], v[124:125]
	v_pk_add_f32 v[246:247], v[246:247], v[126:127]
	v_pk_add_f32 v[244:245], v[244:245], v[140:141]
	v_pk_add_f32 v[246:247], v[246:247], v[142:143]
	v_add_f32_e32 v244, v80, v244
	v_add_f32_e32 v246, v106, v246
	v_pk_add_f32 v[250:251], v[250:251], v[12:13]
	v_pk_add_f32 v[252:253], v[252:253], v[14:15]
	v_pk_add_f32 v[250:251], v[250:251], v[82:83]
	v_pk_add_f32 v[252:253], v[252:253], v[84:85]
	v_pk_add_f32 v[250:251], v[250:251], v[96:97]
	v_pk_add_f32 v[252:253], v[252:253], v[98:99]
	v_pk_add_f32 v[250:251], v[250:251], v[100:101]
	v_pk_add_f32 v[252:253], v[252:253], v[102:103]
	v_pk_add_f32 v[250:251], v[250:251], v[104:105]
	v_pk_add_f32 v[252:253], v[252:253], v[128:129]
	v_pk_add_f32 v[250:251], v[250:251], v[130:131]
	v_pk_add_f32 v[252:253], v[252:253], v[132:133]
	v_pk_add_f32 v[250:251], v[250:251], v[134:135]
	v_pk_add_f32 v[252:253], v[252:253], v[136:137]
	v_add_f32_e32 v250, v11, v250
	v_add_f32_e32 v252, v237, v252
	v_pk_add_f32 v[240:241], v[240:241], v[86:87]
	v_pk_add_f32 v[240:241], v[240:241], v[138:139]
	s_add_u32 s100, s100, 0x3000
	s_addc_u32 s101, s101, 0
	s_add_u32 s54, s54, 0x80
	s_addc_u32 s55, s55, 0
	s_waitcnt lgkmcnt(0)
	s_barrier
	s_mov_b32 s24, s33
	s_branch .Lf_960
